# ctx-row norm tails: g/scale/shift pieces and split-K gate pieces loaded in one batch instead of one round trip per piece
# speedup vs baseline: 1.0708x; 1.0012x over previous
.LBB0_152:
	s_waitcnt vmcnt(0) lgkmcnt(0)
	v_pk_mul_f32 v[50:51], v[14:15], v[14:15]
	v_pk_mul_f32 v[52:53], v[12:13], v[12:13]
	v_mov_b32_e32 v16, v1
	v_pk_mov_b32 v[54:55], v[52:53], v[50:51] op_sel:[1,0]
	v_mov_b32_e32 v53, v51
	v_mov_b32_e32 v1, v2
	v_mov_b32_e32 v17, v3
	v_pk_mul_f32 v[2:3], v[10:11], v[10:11]
	v_pk_mul_f32 v[18:19], v[8:9], v[8:9]
	v_pk_add_f32 v[50:51], v[54:55], v[52:53]
	flat_load_dwordx4 v[54:57], v[22:23]
	v_pk_add_f32 v[72:73], v[50:51], v[50:51] op_sel_hi:[0,1]
	v_pk_mov_b32 v[50:51], v[18:19], v[2:3] op_sel:[1,0]
	v_mov_b32_e32 v19, v3
	v_pk_add_f32 v[2:3], v[50:51], v[18:19]
	global_load_dwordx4 v[50:53], v[20:21], off
	v_pk_add_f32 v[2:3], v[2:3], v[2:3] op_sel_hi:[0,1]
	v_mul_f32_e32 v2, v4, v4
	v_pk_fma_f32 v[18:19], v[4:5], v[4:5], v[2:3] op_sel_hi:[1,1,0]
	v_mul_f32_e32 v2, v6, v6
	v_pk_fma_f32 v[58:59], v[6:7], v[6:7], v[2:3] op_sel_hi:[1,1,0]
	v_mul_f32_e32 v18, v0, v0
	v_mul_f32_e32 v58, v16, v16
	v_pk_add_f32 v[18:19], v[18:19], v[58:59]
	flat_load_dwordx4 v[58:61], v[24:25]
	global_load_dwordx4 v[104:107], v[20:21], off offset:1024
	flat_load_dwordx4 v[108:111], v[26:27]
	flat_load_dwordx4 v[112:115], v[28:29]
	global_load_dwordx4 v[116:119], v[20:21], off offset:2048
	flat_load_dwordx4 v[120:123], v[30:31]
	flat_load_dwordx4 v[124:127], v[32:33]
	global_load_dwordx4 v[128:131], v[20:21], off offset:3072
	flat_load_dwordx4 v[132:135], v[34:35]
	flat_load_dwordx4 v[136:139], v[36:37]
	v_mul_f32_e32 v72, v1, v1
	v_mul_f32_e32 v2, v17, v17
	v_pk_add_f32 v[2:3], v[72:73], v[2:3]
	s_add_i32 s4, s4, s70
	v_pk_add_f32 v[2:3], v[18:19], v[2:3]
	s_waitcnt vmcnt(0) lgkmcnt(0)
	v_mov_b32_e32 v73, v56
	v_add_f32_e32 v2, v2, v3
	ds_bpermute_b32 v3, v62, v2
	v_mov_b32_e32 v56, v55
	s_waitcnt lgkmcnt(0)
	v_add_f32_e32 v2, v2, v3
	ds_bpermute_b32 v3, v63, v2
	s_waitcnt lgkmcnt(0)
	v_add_f32_e32 v2, v2, v3
	ds_bpermute_b32 v3, v64, v2
	v_mov_b32_e32 v74, v58
	v_mov_b32_e32 v75, v60
	v_mov_b32_e32 v60, v59
	s_waitcnt lgkmcnt(0)
	v_add_f32_e32 v2, v2, v3
	ds_bpermute_b32 v3, v65, v2
	s_waitcnt lgkmcnt(0)
	v_add_f32_e32 v2, v2, v3
	ds_bpermute_b32 v3, v66, v2
	s_waitcnt lgkmcnt(0)
	v_add_f32_e32 v2, v2, v3
	ds_bpermute_b32 v3, v67, v2
	s_waitcnt lgkmcnt(0)
	v_add_f32_e32 v2, v2, v3
	v_fmamk_f32 v2, v2, 0x3a800000, v206
	v_mul_f32_e32 v3, 0x4f800000, v2
	v_cmp_gt_f32_e32 vcc, s57, v2
	s_nop 1
	v_cndmask_b32_e32 v18, v2, v3, vcc
	v_sqrt_f32_e32 v19, v18
	v_mov_b32_e32 v2, v12
	v_mov_b32_e32 v3, v14
	v_add_u32_e32 v12, -1, v19
	v_add_u32_e32 v14, 1, v19
	v_fma_f32 v71, -v12, v19, v18
	v_fma_f32 v72, -v14, v19, v18
	v_cmp_ge_f32_e64 s[0:1], 0, v71
	s_nop 1
	v_cndmask_b32_e64 v12, v19, v12, s[0:1]
	v_cmp_lt_f32_e64 s[0:1], 0, v72
	s_nop 1
	v_cndmask_b32_e64 v12, v12, v14, s[0:1]
	v_mul_f32_e32 v14, 0x37800000, v12
	v_cndmask_b32_e32 v12, v12, v14, vcc
	v_cmp_class_f32_e32 vcc, v18, v207
	v_mov_b32_e32 v14, v13
	s_nop 0
	v_cndmask_b32_e32 v12, v12, v18, vcc
	v_div_scale_f32 v18, s[0:1], v12, v12, 1.0
	v_rcp_f32_e32 v19, v18
	v_div_scale_f32 v13, vcc, 1.0, v12, 1.0
	s_add_i32 s0, s4, 0x4000
	v_fma_f32 v71, -v18, v19, 1.0
	v_fmac_f32_e32 v19, v71, v19
	v_mul_f32_e32 v71, v13, v19
	v_fma_f32 v72, -v18, v71, v13
	v_fmac_f32_e32 v71, v72, v19
	v_fma_f32 v13, -v18, v71, v13
	v_div_fmas_f32 v13, v13, v19, v71
	v_div_fixup_f32 v18, v13, v12, 1.0
	v_pk_mul_f32 v[2:3], v[2:3], v[18:19] op_sel_hi:[1,0]
	v_mov_b32_e32 v12, v50
	v_mov_b32_e32 v13, v52
	v_mov_b32_e32 v72, v54
	v_pk_mul_f32 v[2:3], v[12:13], v[2:3]
	v_pk_add_f32 v[12:13], v[72:73], 1.0 op_sel_hi:[1,0]
	v_mov_b32_e32 v52, v51
	v_pk_fma_f32 v[2:3], v[12:13], v[2:3], v[74:75]
	v_pk_mul_f32 v[12:13], v[14:15], v[18:19] op_sel_hi:[1,0]
	v_pk_add_f32 v[14:15], v[56:57], 1.0 op_sel_hi:[1,0]
	v_pk_mul_f32 v[12:13], v[52:53], v[12:13]
	v_pk_mul_f32 v[0:1], v[0:1], v[18:19] op_sel_hi:[1,0]
	v_pk_fma_f32 v[12:13], v[14:15], v[12:13], v[60:61]
	v_and_b32_sdwa v14, v3, v209 dst_sel:DWORD dst_unused:UNUSED_PAD src0_sel:WORD_1 src1_sel:DWORD
	v_and_b32_sdwa v15, v2, v209 dst_sel:DWORD dst_unused:UNUSED_PAD src0_sel:WORD_1 src1_sel:DWORD
	v_add3_u32 v2, v2, v15, s77
	v_add3_u32 v3, v3, v14, s77
	v_and_b32_sdwa v14, v13, v209 dst_sel:DWORD dst_unused:UNUSED_PAD src0_sel:WORD_1 src1_sel:DWORD
	v_and_b32_sdwa v15, v12, v209 dst_sel:DWORD dst_unused:UNUSED_PAD src0_sel:WORD_1 src1_sel:DWORD
	v_add3_u32 v13, v13, v14, s77
	v_add3_u32 v12, v12, v15, s77
	v_and_b32_e32 v13, 0xffff0000, v13
	v_and_b32_e32 v12, 0xffff0000, v12
	v_or_b32_sdwa v3, v13, v3 dst_sel:DWORD dst_unused:UNUSED_PAD src0_sel:DWORD src1_sel:WORD_1
	v_or_b32_sdwa v2, v12, v2 dst_sel:DWORD dst_unused:UNUSED_PAD src0_sel:DWORD src1_sel:WORD_1
	flat_store_dwordx2 v[48:49], v[2:3]
	v_mov_b32_e32 v3, v10
	v_mov_b32_e32 v10, v9
	v_mov_b32_e32 v2, v8
	v_pk_mul_f32 v[8:9], v[10:11], v[18:19] op_sel_hi:[1,0]
	v_pk_mul_f32 v[2:3], v[2:3], v[18:19] op_sel_hi:[1,0]
	s_cmpk_lt_i32 s0, 0x4200
	v_mov_b32_e32 v12, v104
	v_mov_b32_e32 v13, v105
	v_mov_b32_e32 v14, v106
	v_mov_b32_e32 v15, v107
	v_mov_b32_e32 v50, v108
	v_mov_b32_e32 v51, v109
	v_mov_b32_e32 v52, v110
	v_mov_b32_e32 v53, v111
	v_mov_b32_e32 v54, v112
	v_mov_b32_e32 v55, v113
	v_mov_b32_e32 v56, v114
	v_mov_b32_e32 v57, v115
	v_mov_b32_e32 v11, v14
	s_waitcnt lgkmcnt(0)
	v_mov_b32_e32 v59, v52
	v_mov_b32_e32 v14, v13
	v_mov_b32_e32 v52, v51
	v_mov_b32_e32 v10, v12
	v_mov_b32_e32 v58, v50
	v_mov_b32_e32 v61, v56
	v_mov_b32_e32 v56, v55
	v_pk_mul_f32 v[8:9], v[14:15], v[8:9]
	v_pk_add_f32 v[12:13], v[52:53], 1.0 op_sel_hi:[1,0]
	v_mov_b32_e32 v60, v54
	v_pk_mul_f32 v[2:3], v[10:11], v[2:3]
	v_pk_add_f32 v[10:11], v[58:59], 1.0 op_sel_hi:[1,0]
	v_pk_fma_f32 v[8:9], v[12:13], v[8:9], v[56:57]
	v_pk_fma_f32 v[2:3], v[10:11], v[2:3], v[60:61]
	v_and_b32_sdwa v12, v9, v209 dst_sel:DWORD dst_unused:UNUSED_PAD src0_sel:WORD_1 src1_sel:DWORD
	v_and_b32_sdwa v13, v8, v209 dst_sel:DWORD dst_unused:UNUSED_PAD src0_sel:WORD_1 src1_sel:DWORD
	v_and_b32_sdwa v10, v3, v209 dst_sel:DWORD dst_unused:UNUSED_PAD src0_sel:WORD_1 src1_sel:DWORD
	v_and_b32_sdwa v11, v2, v209 dst_sel:DWORD dst_unused:UNUSED_PAD src0_sel:WORD_1 src1_sel:DWORD
	v_add3_u32 v9, v9, v12, s77
	v_add3_u32 v8, v8, v13, s77
	v_add3_u32 v2, v2, v11, s77
	v_add3_u32 v3, v3, v10, s77
	v_and_b32_e32 v9, 0xffff0000, v9
	v_and_b32_e32 v8, 0xffff0000, v8
	v_or_b32_sdwa v3, v9, v3 dst_sel:DWORD dst_unused:UNUSED_PAD src0_sel:DWORD src1_sel:WORD_1
	v_or_b32_sdwa v2, v8, v2 dst_sel:DWORD dst_unused:UNUSED_PAD src0_sel:DWORD src1_sel:WORD_1
	flat_store_dwordx2 v[48:49], v[2:3] offset:512
	v_mov_b32_e32 v3, v6
	v_mov_b32_e32 v6, v5
	v_mov_b32_e32 v2, v4
	v_pk_mul_f32 v[4:5], v[6:7], v[18:19] op_sel_hi:[1,0]
	v_pk_mul_f32 v[2:3], v[2:3], v[18:19] op_sel_hi:[1,0]
	v_mov_b32_e32 v8, v116
	v_mov_b32_e32 v9, v117
	v_mov_b32_e32 v10, v118
	v_mov_b32_e32 v11, v119
	v_mov_b32_e32 v12, v120
	v_mov_b32_e32 v13, v121
	v_mov_b32_e32 v14, v122
	v_mov_b32_e32 v15, v123
	v_mov_b32_e32 v50, v124
	v_mov_b32_e32 v51, v125
	v_mov_b32_e32 v52, v126
	v_mov_b32_e32 v53, v127
	v_mov_b32_e32 v7, v10
	s_waitcnt lgkmcnt(0)
	v_mov_b32_e32 v55, v14
	v_mov_b32_e32 v10, v9
	v_mov_b32_e32 v14, v13
	v_mov_b32_e32 v6, v8
	v_mov_b32_e32 v54, v12
	v_mov_b32_e32 v57, v52
	v_mov_b32_e32 v52, v51
	v_pk_mul_f32 v[4:5], v[10:11], v[4:5]
	v_pk_add_f32 v[8:9], v[14:15], 1.0 op_sel_hi:[1,0]
	v_mov_b32_e32 v56, v50
	v_pk_mul_f32 v[2:3], v[6:7], v[2:3]
	v_pk_add_f32 v[6:7], v[54:55], 1.0 op_sel_hi:[1,0]
	v_pk_fma_f32 v[4:5], v[8:9], v[4:5], v[52:53]
	v_pk_fma_f32 v[2:3], v[6:7], v[2:3], v[56:57]
	v_and_b32_sdwa v8, v5, v209 dst_sel:DWORD dst_unused:UNUSED_PAD src0_sel:WORD_1 src1_sel:DWORD
	v_and_b32_sdwa v9, v4, v209 dst_sel:DWORD dst_unused:UNUSED_PAD src0_sel:WORD_1 src1_sel:DWORD
	v_and_b32_sdwa v6, v3, v209 dst_sel:DWORD dst_unused:UNUSED_PAD src0_sel:WORD_1 src1_sel:DWORD
	v_and_b32_sdwa v7, v2, v209 dst_sel:DWORD dst_unused:UNUSED_PAD src0_sel:WORD_1 src1_sel:DWORD
	v_add3_u32 v5, v5, v8, s77
	v_add3_u32 v4, v4, v9, s77
	v_add3_u32 v2, v2, v7, s77
	v_add3_u32 v3, v3, v6, s77
	v_and_b32_e32 v5, 0xffff0000, v5
	v_and_b32_e32 v4, 0xffff0000, v4
	v_or_b32_sdwa v3, v5, v3 dst_sel:DWORD dst_unused:UNUSED_PAD src0_sel:DWORD src1_sel:WORD_1
	v_or_b32_sdwa v2, v4, v2 dst_sel:DWORD dst_unused:UNUSED_PAD src0_sel:DWORD src1_sel:WORD_1
	flat_store_dwordx2 v[48:49], v[2:3] offset:1024
	s_nop 0
	v_pk_mul_f32 v[14:15], v[16:17], v[18:19] op_sel_hi:[1,0]
	v_mov_b32_e32 v2, v128
	v_mov_b32_e32 v3, v129
	v_mov_b32_e32 v4, v130
	v_mov_b32_e32 v5, v131
	v_mov_b32_e32 v6, v132
	v_mov_b32_e32 v7, v133
	v_mov_b32_e32 v8, v134
	v_mov_b32_e32 v9, v135
	v_mov_b32_e32 v10, v136
	v_mov_b32_e32 v11, v137
	v_mov_b32_e32 v12, v138
	v_mov_b32_e32 v13, v139
	v_mov_b32_e32 v16, v2
	v_mov_b32_e32 v17, v4
	s_waitcnt lgkmcnt(0)
	v_mov_b32_e32 v18, v6
	v_mov_b32_e32 v19, v8
	v_mov_b32_e32 v4, v3
	v_mov_b32_e32 v8, v7
	v_mov_b32_e32 v50, v10
	v_mov_b32_e32 v51, v12
	v_mov_b32_e32 v12, v11
	v_pk_mul_f32 v[0:1], v[0:1], v[16:17]
	v_pk_add_f32 v[2:3], v[18:19], 1.0 op_sel_hi:[1,0]
	v_pk_mul_f32 v[4:5], v[14:15], v[4:5]
	v_pk_add_f32 v[6:7], v[8:9], 1.0 op_sel_hi:[1,0]
	v_pk_fma_f32 v[0:1], v[0:1], v[2:3], v[50:51]
	v_pk_fma_f32 v[2:3], v[4:5], v[6:7], v[12:13]
	v_and_b32_sdwa v4, v1, v209 dst_sel:DWORD dst_unused:UNUSED_PAD src0_sel:WORD_1 src1_sel:DWORD
	v_and_b32_sdwa v6, v3, v209 dst_sel:DWORD dst_unused:UNUSED_PAD src0_sel:WORD_1 src1_sel:DWORD
	v_and_b32_sdwa v7, v2, v209 dst_sel:DWORD dst_unused:UNUSED_PAD src0_sel:WORD_1 src1_sel:DWORD
	v_and_b32_sdwa v5, v0, v209 dst_sel:DWORD dst_unused:UNUSED_PAD src0_sel:WORD_1 src1_sel:DWORD
	v_add3_u32 v3, v3, v6, s77
	v_add3_u32 v2, v2, v7, s77
	v_add3_u32 v0, v0, v5, s77
	v_add3_u32 v1, v1, v4, s77
	v_and_b32_e32 v3, 0xffff0000, v3
	v_and_b32_e32 v2, 0xffff0000, v2
	v_or_b32_sdwa v1, v3, v1 dst_sel:DWORD dst_unused:UNUSED_PAD src0_sel:DWORD src1_sel:WORD_1
	v_or_b32_sdwa v0, v2, v0 dst_sel:DWORD dst_unused:UNUSED_PAD src0_sel:DWORD src1_sel:WORD_1
	flat_store_dwordx2 v[48:49], v[0:1] offset:1536
	v_lshl_add_u64 v[48:49], v[48:49], 0, s[58:59]
	s_cbranch_scc0 .LBB0_157

.LBB0_722:
	s_waitcnt vmcnt(0) lgkmcnt(0)
	global_load_dwordx4 v[126:129], v[28:29], off
	global_load_dwordx4 v[130:133], v[30:31], off
	global_load_dwordx4 v[134:137], v[34:35], off
	global_load_dwordx4 v[138:141], v[28:29], off offset:1024
	global_load_dwordx4 v[142:145], v[36:37], off
	global_load_dwordx4 v[146:149], v[38:39], off
	global_load_dwordx4 v[150:153], v[28:29], off offset:2048
	global_load_dwordx4 v[154:157], v[40:41], off
	global_load_dwordx4 v[158:161], v[42:43], off
	global_load_dwordx4 v[170:173], v[28:29], off offset:3072
	global_load_dwordx4 v[174:177], v[44:45], off
	global_load_dwordx4 v[178:181], v[46:47], off
	v_pk_mul_f32 v[18:19], v[14:15], v[14:15]
	v_pk_mul_f32 v[20:21], v[12:13], v[12:13]
	v_mov_b32_e32 v58, v1
	v_mov_b32_e32 v1, v2
	v_mov_b32_e32 v59, v3
	v_pk_mul_f32 v[2:3], v[10:11], v[10:11]
	v_pk_mul_f32 v[16:17], v[8:9], v[8:9]
	v_pk_mov_b32 v[22:23], v[20:21], v[18:19] op_sel:[1,0]
	v_mov_b32_e32 v21, v19
	v_pk_add_f32 v[18:19], v[22:23], v[20:21]
	v_pk_mov_b32 v[20:21], v[16:17], v[2:3] op_sel:[1,0]
	v_mov_b32_e32 v17, v3
	v_pk_add_f32 v[2:3], v[20:21], v[16:17]
	v_pk_add_f32 v[18:19], v[18:19], v[18:19] op_sel_hi:[0,1]
	v_pk_add_f32 v[2:3], v[2:3], v[2:3] op_sel_hi:[0,1]
	v_mul_f32_e32 v2, v4, v4
	v_pk_fma_f32 v[16:17], v[4:5], v[4:5], v[2:3] op_sel_hi:[1,1,0]
	v_mul_f32_e32 v2, v6, v6
	v_pk_fma_f32 v[20:21], v[6:7], v[6:7], v[2:3] op_sel_hi:[1,1,0]
	v_mul_f32_e32 v16, v0, v0
	v_mul_f32_e32 v20, v58, v58
	v_mul_f32_e32 v18, v1, v1
	v_mul_f32_e32 v2, v59, v59
	v_pk_add_f32 v[16:17], v[16:17], v[20:21]
	v_pk_add_f32 v[2:3], v[18:19], v[2:3]
	v_mov_b32_e32 v60, v12
	v_pk_add_f32 v[2:3], v[16:17], v[2:3]
	v_mov_b32_e32 v61, v14
	v_add_f32_e32 v2, v2, v3
	ds_bpermute_b32 v3, v120, v2
	v_mov_b32_e32 v14, v13
	s_add_i32 s2, s2, s70
	s_waitcnt lgkmcnt(0)
	v_add_f32_e32 v2, v2, v3
	ds_bpermute_b32 v3, v121, v2
	s_waitcnt lgkmcnt(0)
	v_add_f32_e32 v2, v2, v3
	ds_bpermute_b32 v3, v122, v2
	s_waitcnt lgkmcnt(0)
	v_add_f32_e32 v2, v2, v3
	ds_bpermute_b32 v3, v123, v2
	s_waitcnt lgkmcnt(0)
	v_add_f32_e32 v2, v2, v3
	ds_bpermute_b32 v3, v124, v2
	s_waitcnt lgkmcnt(0)
	v_add_f32_e32 v2, v2, v3
	ds_bpermute_b32 v3, v125, v2
	s_waitcnt lgkmcnt(0)
	v_add_f32_e32 v2, v2, v3
	v_fmamk_f32 v2, v2, 0x3a800000, v206
	v_cmp_gt_f32_e32 vcc, s57, v2
	v_mul_f32_e32 v3, 0x4f800000, v2
	s_nop 0
	v_cndmask_b32_e32 v2, v2, v3, vcc
	v_sqrt_f32_e32 v3, v2
	s_nop 0
	v_add_u32_e32 v16, -1, v3
	v_fma_f32 v17, -v16, v3, v2
	v_cmp_ge_f32_e64 s[0:1], 0, v17
	v_add_u32_e32 v17, 1, v3
	s_nop 0
	v_cndmask_b32_e64 v16, v3, v16, s[0:1]
	v_fma_f32 v3, -v17, v3, v2
	v_cmp_lt_f32_e64 s[0:1], 0, v3
	s_nop 1
	v_cndmask_b32_e64 v3, v16, v17, s[0:1]
	v_mul_f32_e32 v16, 0x37800000, v3
	v_cndmask_b32_e32 v3, v3, v16, vcc
	v_cmp_class_f32_e32 vcc, v2, v207
	s_nop 1
	v_cndmask_b32_e32 v2, v3, v2, vcc
	v_div_scale_f32 v3, s[0:1], v2, v2, 1.0
	v_rcp_f32_e32 v16, v3
	v_readlane_b32 s0, v254, 14
	v_readlane_b32 s1, v254, 15
	s_add_u32 s4, s4, s0
	v_fma_f32 v17, -v3, v16, 1.0
	v_fmac_f32_e32 v16, v17, v16
	v_div_scale_f32 v17, vcc, 1.0, v2, 1.0
	v_mul_f32_e32 v18, v17, v16
	v_fma_f32 v19, -v3, v18, v17
	v_fmac_f32_e32 v18, v19, v16
	v_fma_f32 v3, -v3, v18, v17
	v_div_fmas_f32 v3, v3, v16, v18
	v_div_fixup_f32 v2, v3, v2, 1.0
	v_pk_mul_f32 v[60:61], v[60:61], v[2:3] op_sel_hi:[1,0]
	v_pk_mul_f32 v[12:13], v[14:15], v[2:3] op_sel_hi:[1,0]
	s_addc_u32 s5, s5, s1
	s_add_u32 s6, s6, s0
	s_addc_u32 s7, s7, s1
	s_cmp_lt_i32 s2, s14
	s_waitcnt vmcnt(0) lgkmcnt(0)
	v_mov_b32_e32 v16, v126
	v_mov_b32_e32 v17, v127
	v_mov_b32_e32 v18, v128
	v_mov_b32_e32 v19, v129
	v_mov_b32_e32 v20, v130
	v_mov_b32_e32 v21, v131
	v_mov_b32_e32 v22, v132
	v_mov_b32_e32 v23, v133
	v_mov_b32_e32 v24, v134
	v_mov_b32_e32 v25, v135
	v_mov_b32_e32 v26, v136
	v_mov_b32_e32 v27, v137
	v_mov_b32_e32 v62, v16
	v_mov_b32_e32 v63, v18
	v_pk_mul_f32 v[60:61], v[62:63], v[60:61]
	s_waitcnt lgkmcnt(0)
	v_mov_b32_e32 v63, v22
	v_mov_b32_e32 v18, v17
	v_mov_b32_e32 v22, v21
	v_mov_b32_e32 v62, v20
	v_mov_b32_e32 v65, v26
	v_pk_mul_f32 v[12:13], v[18:19], v[12:13]
	v_pk_add_f32 v[14:15], v[22:23], 1.0 op_sel_hi:[1,0]
	v_mov_b32_e32 v26, v25
	v_pk_add_f32 v[62:63], v[62:63], 1.0 op_sel_hi:[1,0]
	v_mov_b32_e32 v64, v24
	v_pk_fma_f32 v[12:13], v[14:15], v[12:13], v[26:27]
	v_pk_fma_f32 v[60:61], v[62:63], v[60:61], v[64:65]
	v_and_b32_sdwa v15, v13, v209 dst_sel:DWORD dst_unused:UNUSED_PAD src0_sel:WORD_1 src1_sel:DWORD
	v_and_b32_sdwa v16, v12, v209 dst_sel:DWORD dst_unused:UNUSED_PAD src0_sel:WORD_1 src1_sel:DWORD
	v_and_b32_sdwa v3, v61, v209 dst_sel:DWORD dst_unused:UNUSED_PAD src0_sel:WORD_1 src1_sel:DWORD
	v_and_b32_sdwa v14, v60, v209 dst_sel:DWORD dst_unused:UNUSED_PAD src0_sel:WORD_1 src1_sel:DWORD
	v_add3_u32 v13, v13, v15, s77
	v_add3_u32 v12, v12, v16, s77
	v_add3_u32 v14, v60, v14, s77
	v_add3_u32 v3, v61, v3, s77
	v_and_b32_e32 v13, 0xffff0000, v13
	v_and_b32_e32 v12, 0xffff0000, v12
	v_or_b32_sdwa v13, v13, v3 dst_sel:DWORD dst_unused:UNUSED_PAD src0_sel:DWORD src1_sel:WORD_1
	v_or_b32_sdwa v12, v12, v14 dst_sel:DWORD dst_unused:UNUSED_PAD src0_sel:DWORD src1_sel:WORD_1
	flat_store_dwordx2 v[56:57], v[12:13]
	s_nop 0
	v_mov_b32_e32 v24, v8
	v_mov_b32_e32 v25, v10
	v_pk_mul_f32 v[24:25], v[24:25], v[2:3] op_sel_hi:[1,0]
	v_mov_b32_e32 v10, v9
	v_pk_mul_f32 v[8:9], v[10:11], v[2:3] op_sel_hi:[1,0]
	v_mov_b32_e32 v12, v138
	v_mov_b32_e32 v13, v139
	v_mov_b32_e32 v14, v140
	v_mov_b32_e32 v15, v141
	v_mov_b32_e32 v16, v142
	v_mov_b32_e32 v17, v143
	v_mov_b32_e32 v18, v144
	v_mov_b32_e32 v19, v145
	v_mov_b32_e32 v20, v146
	v_mov_b32_e32 v21, v147
	v_mov_b32_e32 v22, v148
	v_mov_b32_e32 v23, v149
	v_mov_b32_e32 v26, v12
	v_mov_b32_e32 v27, v14
	v_pk_mul_f32 v[24:25], v[26:27], v[24:25]
	s_waitcnt lgkmcnt(0)
	v_mov_b32_e32 v27, v18
	v_mov_b32_e32 v14, v13
	v_mov_b32_e32 v18, v17
	v_mov_b32_e32 v26, v16
	v_mov_b32_e32 v61, v22
	v_pk_mul_f32 v[8:9], v[14:15], v[8:9]
	v_pk_add_f32 v[10:11], v[18:19], 1.0 op_sel_hi:[1,0]
	v_mov_b32_e32 v22, v21
	v_pk_add_f32 v[26:27], v[26:27], 1.0 op_sel_hi:[1,0]
	v_mov_b32_e32 v60, v20
	v_pk_fma_f32 v[8:9], v[10:11], v[8:9], v[22:23]
	v_pk_fma_f32 v[24:25], v[26:27], v[24:25], v[60:61]
	v_and_b32_sdwa v11, v9, v209 dst_sel:DWORD dst_unused:UNUSED_PAD src0_sel:WORD_1 src1_sel:DWORD
	v_and_b32_sdwa v12, v8, v209 dst_sel:DWORD dst_unused:UNUSED_PAD src0_sel:WORD_1 src1_sel:DWORD
	v_and_b32_sdwa v3, v25, v209 dst_sel:DWORD dst_unused:UNUSED_PAD src0_sel:WORD_1 src1_sel:DWORD
	v_and_b32_sdwa v10, v24, v209 dst_sel:DWORD dst_unused:UNUSED_PAD src0_sel:WORD_1 src1_sel:DWORD
	v_add3_u32 v9, v9, v11, s77
	v_add3_u32 v8, v8, v12, s77
	v_add3_u32 v10, v24, v10, s77
	v_add3_u32 v3, v25, v3, s77
	v_and_b32_e32 v9, 0xffff0000, v9
	v_and_b32_e32 v8, 0xffff0000, v8
	v_or_b32_sdwa v9, v9, v3 dst_sel:DWORD dst_unused:UNUSED_PAD src0_sel:DWORD src1_sel:WORD_1
	v_or_b32_sdwa v8, v8, v10 dst_sel:DWORD dst_unused:UNUSED_PAD src0_sel:DWORD src1_sel:WORD_1
	flat_store_dwordx2 v[56:57], v[8:9] offset:512
	s_nop 0
	v_mov_b32_e32 v20, v4
	v_mov_b32_e32 v21, v6
	v_pk_mul_f32 v[20:21], v[20:21], v[2:3] op_sel_hi:[1,0]
	v_mov_b32_e32 v6, v5
	v_pk_mul_f32 v[4:5], v[6:7], v[2:3] op_sel_hi:[1,0]
	v_mov_b32_e32 v8, v150
	v_mov_b32_e32 v9, v151
	v_mov_b32_e32 v10, v152
	v_mov_b32_e32 v11, v153
	v_mov_b32_e32 v12, v154
	v_mov_b32_e32 v13, v155
	v_mov_b32_e32 v14, v156
	v_mov_b32_e32 v15, v157
	v_mov_b32_e32 v16, v158
	v_mov_b32_e32 v17, v159
	v_mov_b32_e32 v18, v160
	v_mov_b32_e32 v19, v161
	v_mov_b32_e32 v22, v8
	v_mov_b32_e32 v23, v10
	v_pk_mul_f32 v[20:21], v[22:23], v[20:21]
	s_waitcnt lgkmcnt(0)
	v_mov_b32_e32 v23, v14
	v_mov_b32_e32 v10, v9
	v_mov_b32_e32 v14, v13
	v_mov_b32_e32 v22, v12
	v_mov_b32_e32 v25, v18
	v_pk_mul_f32 v[4:5], v[10:11], v[4:5]
	v_pk_add_f32 v[6:7], v[14:15], 1.0 op_sel_hi:[1,0]
	v_mov_b32_e32 v18, v17
	v_pk_add_f32 v[22:23], v[22:23], 1.0 op_sel_hi:[1,0]
	v_mov_b32_e32 v24, v16
	v_pk_fma_f32 v[4:5], v[6:7], v[4:5], v[18:19]
	v_pk_fma_f32 v[20:21], v[22:23], v[20:21], v[24:25]
	v_and_b32_sdwa v7, v5, v209 dst_sel:DWORD dst_unused:UNUSED_PAD src0_sel:WORD_1 src1_sel:DWORD
	v_and_b32_sdwa v8, v4, v209 dst_sel:DWORD dst_unused:UNUSED_PAD src0_sel:WORD_1 src1_sel:DWORD
	v_and_b32_sdwa v3, v21, v209 dst_sel:DWORD dst_unused:UNUSED_PAD src0_sel:WORD_1 src1_sel:DWORD
	v_and_b32_sdwa v6, v20, v209 dst_sel:DWORD dst_unused:UNUSED_PAD src0_sel:WORD_1 src1_sel:DWORD
	v_add3_u32 v5, v5, v7, s77
	v_add3_u32 v4, v4, v8, s77
	v_add3_u32 v6, v20, v6, s77
	v_add3_u32 v3, v21, v3, s77
	v_and_b32_e32 v5, 0xffff0000, v5
	v_and_b32_e32 v4, 0xffff0000, v4
	v_or_b32_sdwa v5, v5, v3 dst_sel:DWORD dst_unused:UNUSED_PAD src0_sel:DWORD src1_sel:WORD_1
	v_or_b32_sdwa v4, v4, v6 dst_sel:DWORD dst_unused:UNUSED_PAD src0_sel:DWORD src1_sel:WORD_1
	flat_store_dwordx2 v[56:57], v[4:5] offset:1024
	s_nop 0
	v_pk_mul_f32 v[0:1], v[0:1], v[2:3] op_sel_hi:[1,0]
	v_pk_mul_f32 v[2:3], v[58:59], v[2:3] op_sel_hi:[1,0]
	v_mov_b32_e32 v4, v170
	v_mov_b32_e32 v5, v171
	v_mov_b32_e32 v6, v172
	v_mov_b32_e32 v7, v173
	v_mov_b32_e32 v8, v174
	v_mov_b32_e32 v9, v175
	v_mov_b32_e32 v10, v176
	v_mov_b32_e32 v11, v177
	v_mov_b32_e32 v12, v178
	v_mov_b32_e32 v13, v179
	v_mov_b32_e32 v14, v180
	v_mov_b32_e32 v15, v181
	v_mov_b32_e32 v16, v4
	v_mov_b32_e32 v17, v6
	v_pk_mul_f32 v[0:1], v[0:1], v[16:17]
	s_waitcnt lgkmcnt(0)
	v_mov_b32_e32 v16, v8
	v_mov_b32_e32 v17, v10
	v_pk_add_f32 v[16:17], v[16:17], 1.0 op_sel_hi:[1,0]
	v_mov_b32_e32 v18, v12
	v_mov_b32_e32 v19, v14
	v_mov_b32_e32 v6, v5
	v_mov_b32_e32 v10, v9
	v_pk_fma_f32 v[0:1], v[0:1], v[16:17], v[18:19]
	v_pk_mul_f32 v[2:3], v[2:3], v[6:7]
	v_pk_add_f32 v[4:5], v[10:11], 1.0 op_sel_hi:[1,0]
	v_mov_b32_e32 v14, v13
	v_pk_fma_f32 v[2:3], v[2:3], v[4:5], v[14:15]
	v_and_b32_sdwa v4, v1, v209 dst_sel:DWORD dst_unused:UNUSED_PAD src0_sel:WORD_1 src1_sel:DWORD
	v_and_b32_sdwa v5, v0, v209 dst_sel:DWORD dst_unused:UNUSED_PAD src0_sel:WORD_1 src1_sel:DWORD
	v_add3_u32 v0, v0, v5, s77
	v_add3_u32 v1, v1, v4, s77
	v_and_b32_sdwa v4, v3, v209 dst_sel:DWORD dst_unused:UNUSED_PAD src0_sel:WORD_1 src1_sel:DWORD
	v_and_b32_sdwa v5, v2, v209 dst_sel:DWORD dst_unused:UNUSED_PAD src0_sel:WORD_1 src1_sel:DWORD
	v_add3_u32 v3, v3, v4, s77
	v_add3_u32 v2, v2, v5, s77
	v_and_b32_e32 v3, 0xffff0000, v3
	v_and_b32_e32 v2, 0xffff0000, v2
	v_or_b32_sdwa v1, v3, v1 dst_sel:DWORD dst_unused:UNUSED_PAD src0_sel:DWORD src1_sel:WORD_1
	v_or_b32_sdwa v0, v2, v0 dst_sel:DWORD dst_unused:UNUSED_PAD src0_sel:DWORD src1_sel:WORD_1
	flat_store_dwordx2 v[56:57], v[0:1] offset:1536
	v_lshl_add_u64 v[56:57], v[56:57], 0, s[58:59]
	s_cbranch_scc0 .LBB0_725
.LBB0_723:
	v_lshl_add_u64 v[16:17], s[4:5], 0, v[32:33]
	v_add_co_u32_e32 v0, vcc, 0xcf00000, v16
	s_nop 1
	v_addc_co_u32_e32 v1, vcc, 0, v17, vcc
	flat_load_dwordx4 v[12:15], v[0:1]
	flat_load_dwordx4 v[8:11], v[0:1] offset:1024
	flat_load_dwordx4 v[4:7], v[0:1] offset:2048
	s_nop 0
	flat_load_dwordx4 v[0:3], v[0:1] offset:3072
	s_andn2_b64 vcc, exec, s[52:53]
	s_cbranch_vccnz .LBB0_722
	v_lshl_add_u64 v[26:27], s[6:7], 0, v[32:33]
	v_add_co_u32_e32 v78, vcc, 0xe900000, v26
	s_mov_b64 s[0:1], 0xcf00000
	s_nop 0
	v_addc_co_u32_e32 v79, vcc, 0, v27, vcc
	v_add_co_u32_e32 v90, vcc, 0xeb00000, v26
	global_load_dwordx4 v[18:21], v[78:79], off
	s_nop 0
	v_addc_co_u32_e32 v91, vcc, 0, v27, vcc
	v_add_co_u32_e32 v102, vcc, 0xed00000, v26
	global_load_dwordx4 v[22:25], v[90:91], off
	s_nop 0
	v_addc_co_u32_e32 v103, vcc, 0, v27, vcc
	global_load_dwordx4 v[58:61], v[102:103], off
	v_add_co_u32_e32 v26, vcc, 0xef00000, v26
	v_lshl_add_u64 v[118:119], v[16:17], 0, s[0:1]
	s_nop 0
	v_addc_co_u32_e32 v27, vcc, 0, v27, vcc
	global_load_dwordx4 v[62:65], v[26:27], off
	flat_load_dwordx4 v[66:69], v[48:49]
	global_load_dwordx4 v[182:185], v[50:51], off
	global_load_dwordx4 v[186:189], v[52:53], off
	global_load_dwordx4 v[190:193], v[54:55], off
	global_load_dwordx4 v[70:73], v[78:79], off offset:1024
	global_load_dwordx4 v[74:77], v[78:79], off offset:2048
	s_nop 0
	global_load_dwordx4 v[78:81], v[78:79], off offset:3072
	s_nop 0
	global_load_dwordx4 v[82:85], v[90:91], off offset:1024
	global_load_dwordx4 v[86:89], v[90:91], off offset:2048
	s_nop 0
	global_load_dwordx4 v[90:93], v[90:91], off offset:3072
	s_nop 0
	global_load_dwordx4 v[94:97], v[102:103], off offset:1024
	global_load_dwordx4 v[98:101], v[102:103], off offset:2048
	s_nop 0
	global_load_dwordx4 v[102:105], v[102:103], off offset:3072
	s_nop 0
	global_load_dwordx4 v[106:109], v[26:27], off offset:1024
	global_load_dwordx4 v[110:113], v[26:27], off offset:2048
	global_load_dwordx4 v[114:117], v[26:27], off offset:3072
	s_mov_b64 s[0:1], 0xcf00400
	s_waitcnt vmcnt(0)
	v_pk_add_f32 v[18:19], v[18:19], 0 op_sel_hi:[1,0]
	v_pk_add_f32 v[20:21], v[20:21], 0 op_sel_hi:[1,0]
	v_pk_add_f32 v[26:27], v[72:73], 0 op_sel_hi:[1,0]
	v_pk_add_f32 v[18:19], v[18:19], v[22:23]
	v_pk_add_f32 v[20:21], v[20:21], v[24:25]
	v_pk_add_f32 v[24:25], v[70:71], 0 op_sel_hi:[1,0]
	v_pk_add_f32 v[18:19], v[18:19], v[58:59]
	v_pk_add_f32 v[20:21], v[20:21], v[60:61]
	v_pk_add_f32 v[24:25], v[24:25], v[82:83]
	v_pk_add_f32 v[26:27], v[26:27], v[84:85]
	v_pk_add_f32 v[24:25], v[24:25], v[94:95]
	v_pk_add_f32 v[18:19], v[18:19], v[62:63]
	v_pk_add_f32 v[20:21], v[20:21], v[64:65]
	s_waitcnt lgkmcnt(0)
	v_pk_fma_f32 v[12:13], v[18:19], v[66:67], v[12:13]
	v_pk_fma_f32 v[14:15], v[20:21], v[68:69], v[14:15]
	flat_store_dwordx4 v[118:119], v[12:15]
	v_pk_add_f32 v[26:27], v[26:27], v[96:97]
	v_pk_add_f32 v[24:25], v[24:25], v[106:107]
	v_pk_add_f32 v[26:27], v[26:27], v[108:109]
	v_lshl_add_u64 v[22:23], v[16:17], 0, s[0:1]
	s_mov_b64 s[0:1], 0xcf00800
	v_pk_fma_f32 v[8:9], v[24:25], v[182:183], v[8:9]
	v_pk_fma_f32 v[10:11], v[26:27], v[184:185], v[10:11]
	flat_store_dwordx4 v[22:23], v[8:11]
	v_pk_add_f32 v[24:25], v[74:75], 0 op_sel_hi:[1,0]
	v_pk_add_f32 v[26:27], v[76:77], 0 op_sel_hi:[1,0]
	v_pk_add_f32 v[24:25], v[24:25], v[86:87]
	v_pk_add_f32 v[26:27], v[26:27], v[88:89]
	v_pk_add_f32 v[24:25], v[24:25], v[98:99]
	v_pk_add_f32 v[26:27], v[26:27], v[100:101]
	v_pk_add_f32 v[24:25], v[24:25], v[110:111]
	v_pk_add_f32 v[26:27], v[26:27], v[112:113]
	v_lshl_add_u64 v[22:23], v[16:17], 0, s[0:1]
	s_mov_b64 s[0:1], 0xcf00c00
	v_lshl_add_u64 v[16:17], v[16:17], 0, s[0:1]
	v_pk_fma_f32 v[4:5], v[24:25], v[186:187], v[4:5]
	v_pk_fma_f32 v[6:7], v[26:27], v[188:189], v[6:7]
	flat_store_dwordx4 v[22:23], v[4:7]
	v_pk_add_f32 v[22:23], v[78:79], 0 op_sel_hi:[1,0]
	v_pk_add_f32 v[24:25], v[80:81], 0 op_sel_hi:[1,0]
	v_pk_add_f32 v[22:23], v[22:23], v[90:91]
	v_pk_add_f32 v[24:25], v[24:25], v[92:93]
	v_pk_add_f32 v[22:23], v[22:23], v[102:103]
	v_pk_add_f32 v[24:25], v[24:25], v[104:105]
	v_pk_add_f32 v[22:23], v[22:23], v[114:115]
	v_pk_add_f32 v[24:25], v[24:25], v[116:117]
	v_pk_fma_f32 v[0:1], v[22:23], v[190:191], v[0:1]
	v_pk_fma_f32 v[2:3], v[24:25], v[192:193], v[2:3]
	flat_store_dwordx4 v[16:17], v[0:3]
	s_branch .LBB0_722
